# prologue pooling-weight fold rewritten with f32-operand MFMA (v_mfma_f32_32x32x2_f32), 2 waves per WG, replaces VMEM-issue-bound per-thread loop
# baseline (speedup 1.0000x reference)
; __device__ __forceinline__ unsigned f2bf(float f) { return pg8::cvt_pk_bf16(f, 0.f) & 0xffffu; }
; __device__ __forceinline__ void prologue(const Params& p, LAS unsigned char* lds, int gw, int ngw, int wave, int lane) {
;     ...
;     {
;         const float* pw = p.in[I_ABPW]; const float* ps = p.in[I_ABPS]; const float* wo = p.in[I_ABWOUT] + (size_t)512 * 1024;
;         bf16* WT = (bf16*)(ws + W_WOUT);
;         const int gt = gw * 64 + lane, ngt = ngw * 64;
;         for (int o = gt; o < 128 * 1024; o += ngt) {
;             const int n = o & 1023, d = o >> 10;
;             float a[4] = {0.f, 0.f, 0.f, 0.f};
; #pragma unroll 4
;             for (int e = 0; e < 128; ++e) {
; #pragma unroll
;                 for (int g = 0; g < 4; ++g) a[g] += pw[((size_t)g * 128 + d) * 128 + e] * ps[g * 128 + e] * wo[((size_t)g * 128 + e) * 1024 + n]; }
; #pragma unroll
;             for (int g = 0; g < 4; ++g) WT[(size_t)n * 1024 + 512 + g * 128 + d] = (bf16)f2bf(a[g]); }
;     }
.LBB0_46:
	v_readlane_b32 s0, v240, 1
	v_lshl_or_b32 v54, s33, 6, v52
	s_mov_b32 s3, 0x20000
	v_readlane_b32 s1, v240, 2
	s_lshl_b32 s2, s0, 9
	v_cmp_gt_i32_e32 vcc, s3, v54
	s_mov_b64 exec, -1
	v_and_b32_e32 v1, 31, v52
	v_lshrrev_b32_e32 v14, 5, v52
	v_lshlrev_b32_e32 v10, 9, v1
	v_lshl_add_u32 v10, v14, 4, v10
	v_lshlrev_b32_e32 v11, 4, v14
	v_lshlrev_b32_e32 v12, 2, v1
	v_lshl_add_u32 v12, v14, 14, v12
	v_lshlrev_b32_e32 v13, 11, v1
	v_lshl_add_u32 v13, v14, 3, v13
	s_and_b32 s34, s33, 7
	s_cmp_gt_u32 s34, 1
	s_cbranch_scc1 .Lfold_done
	s_lshr_b32 s28, s33, 3
	s_lshl_b32 s28, s28, 1
	s_add_u32 s28, s28, s34
	s_lshr_b32 s29, s2, 8
.Lfold_task:
	s_cmp_gt_u32 s28, 0x1ff
	s_cbranch_scc1 .Lfold_done
	s_lshr_b32 s34, s28, 7
	s_bfe_u32 s35, s28, 0x20005
	s_and_b32 s38, s28, 31
	s_lshl_b32 s39, s34, 16
	s_lshl_b32 s40, s35, 14
	s_add_u32 s39, s39, s40
	s_add_u32 s4, s14, s39
	s_addc_u32 s5, s15, 0
	s_lshl_b32 s39, s34, 9
	s_add_u32 s8, s16, s39
	s_addc_u32 s9, s17, 0
	s_lshl_b32 s39, s34, 19
	s_lshl_b32 s40, s38, 7
	s_add_u32 s39, s39, s40
	s_add_u32 s39, s39, 0x200000
	s_add_u32 s10, s18, s39
	s_addc_u32 s11, s19, 0
	s_lshl_b32 s39, s38, 16
	s_lshl_b32 s40, s34, 8
	s_add_u32 s39, s39, s40
	s_lshl_b32 s40, s35, 6
	s_add_u32 s39, s39, s40
	s_add_u32 s39, s39, 0x300400
	s_add_u32 s20, s94, s39
	s_addc_u32 s21, s95, 0
	v_mov_b32_e32 v16, 0
	v_mov_b32_e32 v17, 0
	v_mov_b32_e32 v18, 0
	v_mov_b32_e32 v19, 0
	v_mov_b32_e32 v20, 0
	v_mov_b32_e32 v21, 0
	v_mov_b32_e32 v22, 0
	v_mov_b32_e32 v23, 0
	v_mov_b32_e32 v24, 0
	v_mov_b32_e32 v25, 0
	v_mov_b32_e32 v26, 0
	v_mov_b32_e32 v27, 0
	v_mov_b32_e32 v28, 0
	v_mov_b32_e32 v29, 0
	v_mov_b32_e32 v30, 0
	v_mov_b32_e32 v31, 0
	global_load_dwordx4 v[32:35], v10, s[4:5] offset:0
	global_load_dwordx4 v[36:39], v10, s[4:5] offset:32
	global_load_dwordx4 v[40:43], v11, s[8:9] offset:0
	global_load_dwordx4 v[44:47], v11, s[8:9] offset:32
	global_load_dword v56, v12, s[10:11]
	s_add_u32 s10, s10, 0x1000
	s_addc_u32 s11, s11, 0
	global_load_dword v57, v12, s[10:11]
	s_add_u32 s10, s10, 0x1000
	s_addc_u32 s11, s11, 0
	global_load_dword v58, v12, s[10:11]
	s_add_u32 s10, s10, 0x1000
	s_addc_u32 s11, s11, 0
	global_load_dword v59, v12, s[10:11]
	s_add_u32 s10, s10, 0x5000
	s_addc_u32 s11, s11, 0
	global_load_dword v60, v12, s[10:11]
	s_add_u32 s10, s10, 0x1000
	s_addc_u32 s11, s11, 0
	global_load_dword v61, v12, s[10:11]
	s_add_u32 s10, s10, 0x1000
	s_addc_u32 s11, s11, 0
	global_load_dword v62, v12, s[10:11]
	s_add_u32 s10, s10, 0x1000
	s_addc_u32 s11, s11, 0
	global_load_dword v63, v12, s[10:11]
	s_add_u32 s10, s10, 0x5000
	s_addc_u32 s11, s11, 0
	global_load_dwordx4 v[64:67], v10, s[4:5] offset:64
	global_load_dwordx4 v[68:71], v10, s[4:5] offset:96
	global_load_dwordx4 v[2:5], v11, s[8:9] offset:64
	global_load_dwordx4 v[6:9], v11, s[8:9] offset:96
	global_load_dword v72, v12, s[10:11]
	s_add_u32 s10, s10, 0x1000
	s_addc_u32 s11, s11, 0
	global_load_dword v73, v12, s[10:11]
	s_add_u32 s10, s10, 0x1000
	s_addc_u32 s11, s11, 0
	global_load_dword v74, v12, s[10:11]
	s_add_u32 s10, s10, 0x1000
	s_addc_u32 s11, s11, 0
	global_load_dword v75, v12, s[10:11]
	s_add_u32 s10, s10, 0x5000
	s_addc_u32 s11, s11, 0
	global_load_dword v76, v12, s[10:11]
	s_add_u32 s10, s10, 0x1000
	s_addc_u32 s11, s11, 0
	global_load_dword v77, v12, s[10:11]
	s_add_u32 s10, s10, 0x1000
	s_addc_u32 s11, s11, 0
	global_load_dword v48, v12, s[10:11]
	s_add_u32 s10, s10, 0x1000
	s_addc_u32 s11, s11, 0
	global_load_dword v49, v12, s[10:11]
	s_add_u32 s10, s10, 0x5000
	s_addc_u32 s11, s11, 0
	s_waitcnt vmcnt(12)
	v_mul_f32_e32 v32, v32, v40
	v_mul_f32_e32 v33, v33, v41
	v_mul_f32_e32 v34, v34, v42
	v_mul_f32_e32 v35, v35, v43
	v_mul_f32_e32 v36, v36, v44
	v_mul_f32_e32 v37, v37, v45
	v_mul_f32_e32 v38, v38, v46
	v_mul_f32_e32 v39, v39, v47
	v_mfma_f32_32x32x2_f32 v[16:31], v32, v56, v[16:31]
	v_mfma_f32_32x32x2_f32 v[16:31], v33, v57, v[16:31]
	v_mfma_f32_32x32x2_f32 v[16:31], v34, v58, v[16:31]
	v_mfma_f32_32x32x2_f32 v[16:31], v35, v59, v[16:31]
	v_mfma_f32_32x32x2_f32 v[16:31], v36, v60, v[16:31]
	v_mfma_f32_32x32x2_f32 v[16:31], v37, v61, v[16:31]
	v_mfma_f32_32x32x2_f32 v[16:31], v38, v62, v[16:31]
	v_mfma_f32_32x32x2_f32 v[16:31], v39, v63, v[16:31]
	global_load_dwordx4 v[32:35], v10, s[4:5] offset:128
	global_load_dwordx4 v[36:39], v10, s[4:5] offset:160
	global_load_dwordx4 v[40:43], v11, s[8:9] offset:128
	global_load_dwordx4 v[44:47], v11, s[8:9] offset:160
	global_load_dword v56, v12, s[10:11]
	s_add_u32 s10, s10, 0x1000
	s_addc_u32 s11, s11, 0
	global_load_dword v57, v12, s[10:11]
	s_add_u32 s10, s10, 0x1000
	s_addc_u32 s11, s11, 0
	global_load_dword v58, v12, s[10:11]
	s_add_u32 s10, s10, 0x1000
	s_addc_u32 s11, s11, 0
	global_load_dword v59, v12, s[10:11]
	s_add_u32 s10, s10, 0x5000
	s_addc_u32 s11, s11, 0
	global_load_dword v60, v12, s[10:11]
	s_add_u32 s10, s10, 0x1000
	s_addc_u32 s11, s11, 0
	global_load_dword v61, v12, s[10:11]
	s_add_u32 s10, s10, 0x1000
	s_addc_u32 s11, s11, 0
	global_load_dword v62, v12, s[10:11]
	s_add_u32 s10, s10, 0x1000
	s_addc_u32 s11, s11, 0
	global_load_dword v63, v12, s[10:11]
	s_add_u32 s10, s10, 0x5000
	s_addc_u32 s11, s11, 0
	s_waitcnt vmcnt(12)
; __device__ __forceinline__ unsigned f2bf(float f) { return pg8::cvt_pk_bf16(f, 0.f) & 0xffffu; }
; __device__ __forceinline__ void prologue(const Params& p, LAS unsigned char* lds, int gw, int ngw, int wave, int lane) {
;     ...
;             for (int e = 0; e < 128; ++e) {
; #pragma unroll
;                 for (int g = 0; g < 4; ++g) a[g] += pw[((size_t)g * 128 + d) * 128 + e] * ps[g * 128 + e] * wo[((size_t)g * 128 + e) * 1024 + n]; }
; #pragma unroll
;             for (int g = 0; g < 4; ++g) WT[(size_t)n * 1024 + 512 + g * 128 + d] = (bf16)f2bf(a[g]); }
	v_mul_f32_e32 v64, v64, v2
	v_mul_f32_e32 v65, v65, v3
	v_mul_f32_e32 v66, v66, v4
	v_mul_f32_e32 v67, v67, v5
	v_mul_f32_e32 v68, v68, v6
	v_mul_f32_e32 v69, v69, v7
	v_mul_f32_e32 v70, v70, v8
	v_mul_f32_e32 v71, v71, v9
	v_mfma_f32_32x32x2_f32 v[16:31], v64, v72, v[16:31]
	v_mfma_f32_32x32x2_f32 v[16:31], v65, v73, v[16:31]
	v_mfma_f32_32x32x2_f32 v[16:31], v66, v74, v[16:31]
	v_mfma_f32_32x32x2_f32 v[16:31], v67, v75, v[16:31]
	v_mfma_f32_32x32x2_f32 v[16:31], v68, v76, v[16:31]
	v_mfma_f32_32x32x2_f32 v[16:31], v69, v77, v[16:31]
	v_mfma_f32_32x32x2_f32 v[16:31], v70, v48, v[16:31]
	v_mfma_f32_32x32x2_f32 v[16:31], v71, v49, v[16:31]
	global_load_dwordx4 v[64:67], v10, s[4:5] offset:192
	global_load_dwordx4 v[68:71], v10, s[4:5] offset:224
	global_load_dwordx4 v[2:5], v11, s[8:9] offset:192
	global_load_dwordx4 v[6:9], v11, s[8:9] offset:224
	global_load_dword v72, v12, s[10:11]
	s_add_u32 s10, s10, 0x1000
	s_addc_u32 s11, s11, 0
	global_load_dword v73, v12, s[10:11]
	s_add_u32 s10, s10, 0x1000
	s_addc_u32 s11, s11, 0
	global_load_dword v74, v12, s[10:11]
	s_add_u32 s10, s10, 0x1000
	s_addc_u32 s11, s11, 0
	global_load_dword v75, v12, s[10:11]
	s_add_u32 s10, s10, 0x5000
	s_addc_u32 s11, s11, 0
	global_load_dword v76, v12, s[10:11]
	s_add_u32 s10, s10, 0x1000
	s_addc_u32 s11, s11, 0
	global_load_dword v77, v12, s[10:11]
	s_add_u32 s10, s10, 0x1000
	s_addc_u32 s11, s11, 0
	global_load_dword v48, v12, s[10:11]
	s_add_u32 s10, s10, 0x1000
	s_addc_u32 s11, s11, 0
	global_load_dword v49, v12, s[10:11]
	s_add_u32 s10, s10, 0x5000
	s_addc_u32 s11, s11, 0
	s_waitcnt vmcnt(12)
	v_mul_f32_e32 v32, v32, v40
	v_mul_f32_e32 v33, v33, v41
	v_mul_f32_e32 v34, v34, v42
	v_mul_f32_e32 v35, v35, v43
	v_mul_f32_e32 v36, v36, v44
	v_mul_f32_e32 v37, v37, v45
	v_mul_f32_e32 v38, v38, v46
	v_mul_f32_e32 v39, v39, v47
	v_mfma_f32_32x32x2_f32 v[16:31], v32, v56, v[16:31]
	v_mfma_f32_32x32x2_f32 v[16:31], v33, v57, v[16:31]
	v_mfma_f32_32x32x2_f32 v[16:31], v34, v58, v[16:31]
	v_mfma_f32_32x32x2_f32 v[16:31], v35, v59, v[16:31]
	v_mfma_f32_32x32x2_f32 v[16:31], v36, v60, v[16:31]
	v_mfma_f32_32x32x2_f32 v[16:31], v37, v61, v[16:31]
	v_mfma_f32_32x32x2_f32 v[16:31], v38, v62, v[16:31]
	v_mfma_f32_32x32x2_f32 v[16:31], v39, v63, v[16:31]
	global_load_dwordx4 v[32:35], v10, s[4:5] offset:256
	global_load_dwordx4 v[36:39], v10, s[4:5] offset:288
	global_load_dwordx4 v[40:43], v11, s[8:9] offset:256
	global_load_dwordx4 v[44:47], v11, s[8:9] offset:288
	global_load_dword v56, v12, s[10:11]
	s_add_u32 s10, s10, 0x1000
	s_addc_u32 s11, s11, 0
	global_load_dword v57, v12, s[10:11]
	s_add_u32 s10, s10, 0x1000
	s_addc_u32 s11, s11, 0
	global_load_dword v58, v12, s[10:11]
	s_add_u32 s10, s10, 0x1000
	s_addc_u32 s11, s11, 0
	global_load_dword v59, v12, s[10:11]
	s_add_u32 s10, s10, 0x5000
	s_addc_u32 s11, s11, 0
	global_load_dword v60, v12, s[10:11]
	s_add_u32 s10, s10, 0x1000
	s_addc_u32 s11, s11, 0
	global_load_dword v61, v12, s[10:11]
	s_add_u32 s10, s10, 0x1000
	s_addc_u32 s11, s11, 0
	global_load_dword v62, v12, s[10:11]
	s_add_u32 s10, s10, 0x1000
	s_addc_u32 s11, s11, 0
	global_load_dword v63, v12, s[10:11]
	s_add_u32 s10, s10, 0x5000
	s_addc_u32 s11, s11, 0
	s_waitcnt vmcnt(12)
	v_mul_f32_e32 v64, v64, v2
	v_mul_f32_e32 v65, v65, v3
	v_mul_f32_e32 v66, v66, v4
	v_mul_f32_e32 v67, v67, v5
	v_mul_f32_e32 v68, v68, v6
	v_mul_f32_e32 v69, v69, v7
	v_mul_f32_e32 v70, v70, v8
	v_mul_f32_e32 v71, v71, v9
	v_mfma_f32_32x32x2_f32 v[16:31], v64, v72, v[16:31]
	v_mfma_f32_32x32x2_f32 v[16:31], v65, v73, v[16:31]
	v_mfma_f32_32x32x2_f32 v[16:31], v66, v74, v[16:31]
	v_mfma_f32_32x32x2_f32 v[16:31], v67, v75, v[16:31]
	v_mfma_f32_32x32x2_f32 v[16:31], v68, v76, v[16:31]
	v_mfma_f32_32x32x2_f32 v[16:31], v69, v77, v[16:31]
	v_mfma_f32_32x32x2_f32 v[16:31], v70, v48, v[16:31]
	v_mfma_f32_32x32x2_f32 v[16:31], v71, v49, v[16:31]
	global_load_dwordx4 v[64:67], v10, s[4:5] offset:320
	global_load_dwordx4 v[68:71], v10, s[4:5] offset:352
	global_load_dwordx4 v[2:5], v11, s[8:9] offset:320
	global_load_dwordx4 v[6:9], v11, s[8:9] offset:352
	global_load_dword v72, v12, s[10:11]
	s_add_u32 s10, s10, 0x1000
	s_addc_u32 s11, s11, 0
	global_load_dword v73, v12, s[10:11]
	s_add_u32 s10, s10, 0x1000
	s_addc_u32 s11, s11, 0
	global_load_dword v74, v12, s[10:11]
	s_add_u32 s10, s10, 0x1000
	s_addc_u32 s11, s11, 0
	global_load_dword v75, v12, s[10:11]
	s_add_u32 s10, s10, 0x5000
	s_addc_u32 s11, s11, 0
	global_load_dword v76, v12, s[10:11]
	s_add_u32 s10, s10, 0x1000
	s_addc_u32 s11, s11, 0
	global_load_dword v77, v12, s[10:11]
	s_add_u32 s10, s10, 0x1000
	s_addc_u32 s11, s11, 0
	global_load_dword v48, v12, s[10:11]
	s_add_u32 s10, s10, 0x1000
	s_addc_u32 s11, s11, 0
	global_load_dword v49, v12, s[10:11]
	s_add_u32 s10, s10, 0x5000
	s_addc_u32 s11, s11, 0
	s_waitcnt vmcnt(12)
	v_mul_f32_e32 v32, v32, v40
	v_mul_f32_e32 v33, v33, v41
	v_mul_f32_e32 v34, v34, v42
	v_mul_f32_e32 v35, v35, v43
	v_mul_f32_e32 v36, v36, v44
	v_mul_f32_e32 v37, v37, v45
	v_mul_f32_e32 v38, v38, v46
	v_mul_f32_e32 v39, v39, v47
	v_mfma_f32_32x32x2_f32 v[16:31], v32, v56, v[16:31]
	v_mfma_f32_32x32x2_f32 v[16:31], v33, v57, v[16:31]
	v_mfma_f32_32x32x2_f32 v[16:31], v34, v58, v[16:31]
	v_mfma_f32_32x32x2_f32 v[16:31], v35, v59, v[16:31]
	v_mfma_f32_32x32x2_f32 v[16:31], v36, v60, v[16:31]
	v_mfma_f32_32x32x2_f32 v[16:31], v37, v61, v[16:31]
	v_mfma_f32_32x32x2_f32 v[16:31], v38, v62, v[16:31]
	v_mfma_f32_32x32x2_f32 v[16:31], v39, v63, v[16:31]
	global_load_dwordx4 v[32:35], v10, s[4:5] offset:384
	global_load_dwordx4 v[36:39], v10, s[4:5] offset:416
	global_load_dwordx4 v[40:43], v11, s[8:9] offset:384
	global_load_dwordx4 v[44:47], v11, s[8:9] offset:416
	global_load_dword v56, v12, s[10:11]
	s_add_u32 s10, s10, 0x1000
	s_addc_u32 s11, s11, 0
	global_load_dword v57, v12, s[10:11]
	s_add_u32 s10, s10, 0x1000
	s_addc_u32 s11, s11, 0
	global_load_dword v58, v12, s[10:11]
	s_add_u32 s10, s10, 0x1000
	s_addc_u32 s11, s11, 0
	global_load_dword v59, v12, s[10:11]
	s_add_u32 s10, s10, 0x5000
	s_addc_u32 s11, s11, 0
	global_load_dword v60, v12, s[10:11]
	s_add_u32 s10, s10, 0x1000
	s_addc_u32 s11, s11, 0
	global_load_dword v61, v12, s[10:11]
	s_add_u32 s10, s10, 0x1000
	s_addc_u32 s11, s11, 0
	global_load_dword v62, v12, s[10:11]
	s_add_u32 s10, s10, 0x1000
	s_addc_u32 s11, s11, 0
	global_load_dword v63, v12, s[10:11]
	s_add_u32 s10, s10, 0x5000
	s_addc_u32 s11, s11, 0
	s_waitcnt vmcnt(12)
; __device__ __forceinline__ unsigned f2bf(float f) { return pg8::cvt_pk_bf16(f, 0.f) & 0xffffu; }
; __device__ __forceinline__ void prologue(const Params& p, LAS unsigned char* lds, int gw, int ngw, int wave, int lane) {
;     ...
;             for (int e = 0; e < 128; ++e) {
; #pragma unroll
;                 for (int g = 0; g < 4; ++g) a[g] += pw[((size_t)g * 128 + d) * 128 + e] * ps[g * 128 + e] * wo[((size_t)g * 128 + e) * 1024 + n]; }
; #pragma unroll
;             for (int g = 0; g < 4; ++g) WT[(size_t)n * 1024 + 512 + g * 128 + d] = (bf16)f2bf(a[g]); }
;     }
;     for (int m0 = gw * 4; m0 < MT; m0 += ngw * 4) {
;         f32x4 v[4][4];
; #pragma unroll
;         for (int r = 0; r < 4; ++r) { const int m = m0 + r; const f32x4* xr = (const f32x4*)(m < MP ? p.in[I_XP] + (size_t)m * D : p.in[I_XS] + (size_t)(m - MP) * D) + lane;
; #pragma unroll
;             for (int j = 0; j < 4; ++j) v[r][j] = __builtin_nontemporal_load(xr + 64 * j); }
; #pragma unroll
;         for (int r = 0; r < 4; ++r) { const int m = m0 + r; float sq = 0.f;
; #pragma unroll
;             for (int j = 0; j < 4; ++j) sq += (v[r][j].x * v[r][j].x + v[r][j].y * v[r][j].y) + (v[r][j].z * v[r][j].z + v[r][j].w * v[r][j].w);
;             sq = wave_sum(sq);
	v_mul_f32_e32 v64, v64, v2
	v_mul_f32_e32 v65, v65, v3
	v_mul_f32_e32 v66, v66, v4
	v_mul_f32_e32 v67, v67, v5
	v_mul_f32_e32 v68, v68, v6
	v_mul_f32_e32 v69, v69, v7
	v_mul_f32_e32 v70, v70, v8
	v_mul_f32_e32 v71, v71, v9
	v_mfma_f32_32x32x2_f32 v[16:31], v64, v72, v[16:31]
	v_mfma_f32_32x32x2_f32 v[16:31], v65, v73, v[16:31]
	v_mfma_f32_32x32x2_f32 v[16:31], v66, v74, v[16:31]
	v_mfma_f32_32x32x2_f32 v[16:31], v67, v75, v[16:31]
	v_mfma_f32_32x32x2_f32 v[16:31], v68, v76, v[16:31]
	v_mfma_f32_32x32x2_f32 v[16:31], v69, v77, v[16:31]
	v_mfma_f32_32x32x2_f32 v[16:31], v70, v48, v[16:31]
	v_mfma_f32_32x32x2_f32 v[16:31], v71, v49, v[16:31]
	global_load_dwordx4 v[64:67], v10, s[4:5] offset:448
	global_load_dwordx4 v[68:71], v10, s[4:5] offset:480
	global_load_dwordx4 v[2:5], v11, s[8:9] offset:448
	global_load_dwordx4 v[6:9], v11, s[8:9] offset:480
	global_load_dword v72, v12, s[10:11]
	s_add_u32 s10, s10, 0x1000
	s_addc_u32 s11, s11, 0
	global_load_dword v73, v12, s[10:11]
	s_add_u32 s10, s10, 0x1000
	s_addc_u32 s11, s11, 0
	global_load_dword v74, v12, s[10:11]
	s_add_u32 s10, s10, 0x1000
	s_addc_u32 s11, s11, 0
	global_load_dword v75, v12, s[10:11]
	s_add_u32 s10, s10, 0x5000
	s_addc_u32 s11, s11, 0
	global_load_dword v76, v12, s[10:11]
	s_add_u32 s10, s10, 0x1000
	s_addc_u32 s11, s11, 0
	global_load_dword v77, v12, s[10:11]
	s_add_u32 s10, s10, 0x1000
	s_addc_u32 s11, s11, 0
	global_load_dword v48, v12, s[10:11]
	s_add_u32 s10, s10, 0x1000
	s_addc_u32 s11, s11, 0
	global_load_dword v49, v12, s[10:11]
	s_add_u32 s10, s10, 0x5000
	s_addc_u32 s11, s11, 0
	s_waitcnt vmcnt(12)
	v_mul_f32_e32 v32, v32, v40
	v_mul_f32_e32 v33, v33, v41
	v_mul_f32_e32 v34, v34, v42
	v_mul_f32_e32 v35, v35, v43
	v_mul_f32_e32 v36, v36, v44
	v_mul_f32_e32 v37, v37, v45
	v_mul_f32_e32 v38, v38, v46
	v_mul_f32_e32 v39, v39, v47
	v_mfma_f32_32x32x2_f32 v[16:31], v32, v56, v[16:31]
	v_mfma_f32_32x32x2_f32 v[16:31], v33, v57, v[16:31]
	v_mfma_f32_32x32x2_f32 v[16:31], v34, v58, v[16:31]
	v_mfma_f32_32x32x2_f32 v[16:31], v35, v59, v[16:31]
	v_mfma_f32_32x32x2_f32 v[16:31], v36, v60, v[16:31]
	v_mfma_f32_32x32x2_f32 v[16:31], v37, v61, v[16:31]
	v_mfma_f32_32x32x2_f32 v[16:31], v38, v62, v[16:31]
	v_mfma_f32_32x32x2_f32 v[16:31], v39, v63, v[16:31]
	s_waitcnt vmcnt(0)
	v_mul_f32_e32 v64, v64, v2
	v_mul_f32_e32 v65, v65, v3
	v_mul_f32_e32 v66, v66, v4
	v_mul_f32_e32 v67, v67, v5
	v_mul_f32_e32 v68, v68, v6
	v_mul_f32_e32 v69, v69, v7
	v_mul_f32_e32 v70, v70, v8
	v_mul_f32_e32 v71, v71, v9
	v_mfma_f32_32x32x2_f32 v[16:31], v64, v72, v[16:31]
	v_mfma_f32_32x32x2_f32 v[16:31], v65, v73, v[16:31]
	v_mfma_f32_32x32x2_f32 v[16:31], v66, v74, v[16:31]
	v_mfma_f32_32x32x2_f32 v[16:31], v67, v75, v[16:31]
	v_mfma_f32_32x32x2_f32 v[16:31], v68, v76, v[16:31]
	v_mfma_f32_32x32x2_f32 v[16:31], v69, v77, v[16:31]
	v_mfma_f32_32x32x2_f32 v[16:31], v70, v48, v[16:31]
	v_mfma_f32_32x32x2_f32 v[16:31], v71, v49, v[16:31]
	s_nop 15
	s_nop 3
	v_cvt_pk_bf16_f32 v32, v16, v17
	v_cvt_pk_bf16_f32 v33, v18, v19
	global_store_dwordx2 v13, v[32:33], s[20:21]
	v_cvt_pk_bf16_f32 v34, v20, v21
	v_cvt_pk_bf16_f32 v35, v22, v23
	global_store_dwordx2 v13, v[34:35], s[20:21] offset:16
	v_cvt_pk_bf16_f32 v36, v24, v25
	v_cvt_pk_bf16_f32 v37, v26, v27
	global_store_dwordx2 v13, v[36:37], s[20:21] offset:32
	v_cvt_pk_bf16_f32 v38, v28, v29
	v_cvt_pk_bf16_f32 v39, v30, v31
	global_store_dwordx2 v13, v[38:39], s[20:21] offset:48
	s_add_u32 s28, s28, s29
	s_branch .Lfold_task
.Lfold_done:
.LBB0_51:
	s_or_b64 exec, exec, s[0:1]
	s_cmpk_gt_i32 s33, 0x20ff
	v_mbcnt_lo_u32_b32 v217, -1, 0
	s_cbranch_scc1 .LBB0_62
	v_mbcnt_hi_u32_b32 v2, -1, v217
	v_and_b32_e32 v1, 64, v2
	v_add_u32_e32 v3, 64, v1
	v_xor_b32_e32 v1, 1, v2
	v_cmp_lt_i32_e32 vcc, v1, v3
	v_xor_b32_e32 v4, 2, v2
	v_readlane_b32 s0, v240, 1
	v_cndmask_b32_e32 v1, v2, v1, vcc
	v_cmp_lt_i32_e32 vcc, v4, v3
	s_lshl_b32 s8, s33, 2
	v_readlane_b32 s1, v240, 2
	v_cndmask_b32_e32 v4, v2, v4, vcc
	v_lshlrev_b32_e32 v51, 2, v4
	v_xor_b32_e32 v4, 4, v2
	v_cmp_lt_i32_e32 vcc, v4, v3
	s_lshl_b32 s4, s0, 5
	s_ashr_i32 s9, s8, 31
	v_cndmask_b32_e32 v4, v2, v4, vcc
	v_lshlrev_b32_e32 v53, 2, v4
	v_xor_b32_e32 v4, 8, v2
	v_cmp_lt_i32_e32 vcc, v4, v3
	s_ashr_i32 s5, s4, 31
	s_lshl_b64 s[0:1], s[8:9], 11
	v_cndmask_b32_e32 v4, v2, v4, vcc
	v_lshlrev_b32_e32 v55, 2, v4
	v_xor_b32_e32 v4, 16, v2
	v_cmp_lt_i32_e32 vcc, v4, v3
	v_lshlrev_b32_e32 v1, 2, v1
	s_or_b32 s3, s8, 1
	v_cndmask_b32_e32 v4, v2, v4, vcc
	v_lshlrev_b32_e32 v62, 2, v4
	v_xor_b32_e32 v4, 32, v2
	v_cmp_lt_i32_e32 vcc, v4, v3
	s_mov_b32 s18, s9
	s_lshl_b64 s[10:11], s[8:9], 2
	v_cndmask_b32_e32 v2, v2, v4, vcc
	v_lshlrev_b32_e32 v63, 2, v2
	v_cmp_eq_u32_e32 vcc, 0, v52
	s_lshl_b64 s[14:15], s[4:5], 2
	v_lshl_or_b32 v56, v52, 3, s0
	v_mov_b32_e32 v57, s1
	s_lshl_b64 s[16:17], s[4:5], 11
	v_lshlrev_b32_e32 v64, 4, v52
	s_mov_b32 s9, 0x4800000
	v_mov_b32_e32 v65, 0x3f00000
	s_mov_b32 s19, 0x4801000
	s_branch .LBB0_54
